# v49 + sgu prompt items: LayerNorm gain/bias loads hoisted from after the second barrier to the item start
# speedup vs baseline: 1.0010x; 1.0010x over previous
; __device__ __forceinline__ void sgu_prompt_item(int item, const u16* PROJ, u16* MIXIN, const float* gln, const float* bln, const float* wsp, const float* bsp, LAS unsigned char* lds, int& hh_cached) {
;     ...
;     u32x4 rv[4];
; #pragma unroll
;     for (int i = 0; i < 4; ++i) { const int idx = tid + 512 * i, s = idx >> 4, ch = (idx & 15) * 8; rv[i] = *(const u32x4*)(PROJ + (row0 + s) * NPROJ + C_VS + hh * 128 + ch); }
;     u32x2 uw[8];
; #pragma unroll
;     for (int dct = 0; dct < 8; ++dct) uw[dct] = *(const u32x2*)(PROJ + (row0 + 16 * w + (lane & 15)) * NPROJ + C_U + hh * 128 + 16 * dct + (lane >> 4) * 4);
;     const float bs = bsp[hh * 128 + 16 * w + (lane & 15)];
;     ...
;     { const int dc = tid & 127, sg = tid >> 7; const float g = gln[hh * 128 + dc], b = bln[hh * 128 + dc];
.LBB0_236:
	s_ashr_i32 s58, s50, 6
	s_ashr_i32 s59, s58, 31
	s_lshl_b32 s6, s50, 5
	s_lshl_b64 s[78:79], s[58:59], 11
	s_and_b32 s6, s6, 0x780
	s_or_b32 s78, s78, s6
	v_or_b32_e32 v0, s78, v32
	v_mov_b64_e32 v[16:17], s[4:5]
	s_and_b32 s56, s50, 3
	v_mad_u64_u32 v[0:1], s[58:59], v0, s30, v[16:17]
	v_mad_i32_i24 v1, s79, v154, v1
	s_lshl_b32 s6, s56, 8
	v_or_b32_e32 v2, s78, v68
	v_lshl_add_u64 v[0:1], v[0:1], 0, s[6:7]
	v_lshlrev_b32_e32 v52, 1, v60
	v_mad_u64_u32 v[2:3], s[58:59], v2, s30, v[16:17]
	v_readfirstlane_b32 s55, v129
	v_lshl_add_u64 v[0:1], v[0:1], 0, v[52:53]
	v_mad_i32_i24 v3, s79, v154, v3
	v_or_b32_e32 v8, s78, v70
	v_add_co_u32_e32 v0, vcc, s3, v0
	v_lshl_add_u64 v[2:3], v[2:3], 0, s[6:7]
	v_mad_u64_u32 v[8:9], s[58:59], v8, s30, v[16:17]
	s_lshr_b32 s54, s55, 2
	s_lshl_b32 s35, s56, 7
	v_addc_co_u32_e32 v1, vcc, 0, v1, vcc
	v_lshl_add_u64 v[2:3], v[2:3], 0, v[52:53]
	v_mad_i32_i24 v9, s79, v154, v9
	v_lshl_add_u64 v[10:11], s[78:79], 0, v[72:73]
	s_and_b32 s54, s54, 0x3ffffff0
	v_add_co_u32_e32 v4, vcc, s3, v2
	v_lshl_add_u64 v[8:9], v[8:9], 0, s[6:7]
	v_mad_u64_u32 v[12:13], s[58:59], v10, s30, v[16:17]
	s_add_u32 s57, s78, s54
	v_addc_co_u32_e32 v5, vcc, 0, v3, vcc
	v_lshl_add_u64 v[8:9], v[8:9], 0, v[52:53]
	v_mad_i32_i24 v13, v11, s30, v13
	v_or_b32_e32 v18, s57, v64
	v_add_co_u32_e32 v8, vcc, s3, v8
	v_lshl_add_u64 v[10:11], v[12:13], 0, s[6:7]
	s_addc_u32 s60, s79, 0
	v_mad_u64_u32 v[16:17], s[58:59], v18, s30, v[16:17]
	v_addc_co_u32_e32 v9, vcc, 0, v9, vcc
	v_lshl_add_u64 v[10:11], v[10:11], 0, v[52:53]
	v_mad_i32_i24 v17, s60, v154, v17
	v_add_co_u32_e32 v12, vcc, s3, v10
	v_lshl_add_u64 v[16:17], v[16:17], 0, s[6:7]
	v_lshlrev_b32_e32 v102, 1, v66
	v_mov_b32_e32 v103, v53
	v_addc_co_u32_e32 v13, vcc, 0, v11, vcc
	v_lshl_add_u64 v[16:17], v[16:17], 0, v[102:103]
	global_load_dwordx4 v[0:3], v[0:1], off offset:32
	s_nop 0
	global_load_dwordx4 v[4:7], v[4:5], off offset:32
	s_nop 0
	global_load_dwordx4 v[8:11], v[8:9], off offset:32
	s_nop 0
	global_load_dwordx4 v[12:15], v[12:13], off offset:32
	s_nop 0
	global_load_dwordx2 v[104:105], v[16:17], off offset:3104
	global_load_dwordx2 v[100:101], v[16:17], off offset:3136
	global_load_dwordx2 v[98:99], v[16:17], off offset:3168
	global_load_dwordx2 v[96:97], v[16:17], off offset:3200
	global_load_dwordx2 v[94:95], v[16:17], off offset:3232
	global_load_dwordx2 v[92:93], v[16:17], off offset:3264
	global_load_dwordx2 v[90:91], v[16:17], off offset:3296
	global_load_dwordx2 v[88:89], v[16:17], off offset:3328
	s_add_i32 s6, s54, s35
	v_or_b32_e32 v52, s6, v64
	v_lshl_add_u64 v[16:17], v[52:53], 2, s[48:49]
	global_load_dword v79, v[16:17], off
	v_or_b32_e32 v232, s35, v69
	v_lshlrev_b32_e32 v232, 2, v232
	global_load_dword v233, v232, s[42:43]
	global_load_dword v234, v232, s[44:45]
	s_cmp_eq_u32 s56, s51
	s_cbranch_scc1 .LBB0_238
; #define LAS __attribute__((address_space(3)))
; __device__ __forceinline__ unsigned pk2(float lo, float hi) { unsigned r; asm("v_cvt_pk_bf16_f32 %0, %1, %2" : "=v"(r) : "v"(lo), "v"(hi)); return r; }
; __device__ __forceinline__ void sgu_prompt_item(int item, const u16* PROJ, u16* MIXIN, const float* gln, const float* bln, const float* wsp, const float* bsp, LAS unsigned char* lds, int& hh_cached) {
;     ...
;     if (hh != hh_cached) {
;         const int t = tid >> 2, s0 = (tid & 3) * 32; const float* wp = wsp + ((size_t)hh * 128 + t) * 128 + s0;
; #pragma unroll
;         for (int q = 0; q < 4; ++q) { const f32x4 a = *(const f32x4*)(wp + 8 * q), b = *(const f32x4*)(wp + 8 * q + 4); const int s = s0 + 8 * q;
;             u32x4 o; o.x = pk2(s <= t ? a.x : 0.f, s + 1 <= t ? a.y : 0.f); o.y = pk2(s + 2 <= t ? a.z : 0.f, s + 3 <= t ? a.w : 0.f);
;             o.z = pk2(s + 4 <= t ? b.x : 0.f, s + 5 <= t ? b.y : 0.f); o.w = pk2(s + 6 <= t ? b.z : 0.f, s + 7 <= t ? b.w : 0.f);
;             *(LAS u32x4*)(Wm + t * LD2 + s) = o; }
	s_lshl_b32 s6, s56, 14
	v_add_lshl_u32 v52, s6, v119, 2
	v_lshl_add_u64 v[16:17], v[74:75], 0, v[52:53]
	global_load_dwordx4 v[18:21], v[16:17], off offset:16
	global_load_dwordx4 v[22:25], v[16:17], off
	global_load_dwordx4 v[204:207], v[16:17], off offset:48
	global_load_dwordx4 v[208:211], v[16:17], off offset:32
	global_load_dwordx4 v[212:215], v[16:17], off offset:80
	global_load_dwordx4 v[216:219], v[16:17], off offset:64
	global_load_dwordx4 v[220:223], v[16:17], off offset:112
	global_load_dwordx4 v[224:227], v[16:17], off offset:96
	v_readlane_b32 s58, v237, 20
	v_readlane_b32 s59, v237, 21
	s_mov_b32 s51, s56
	s_waitcnt vmcnt(0)
	v_cndmask_b32_e64 v22, v22, 0, s[58:59]
	v_readlane_b32 s58, v237, 22
	v_readlane_b32 s59, v237, 23
	s_nop 1
	v_cndmask_b32_e64 v23, 0, v23, s[58:59]
	v_readlane_b32 s58, v237, 24
	v_readlane_b32 s59, v237, 25
	v_cvt_pk_bf16_f32 v22, v22, v23
	s_nop 1
	v_cndmask_b32_e64 v23, v24, 0, s[58:59]
	v_readlane_b32 s58, v237, 26
	v_readlane_b32 s59, v237, 27
	s_nop 1
	v_cndmask_b32_e64 v24, v25, 0, s[58:59]
	v_readlane_b32 s58, v237, 28
	v_readlane_b32 s59, v237, 29
	v_cvt_pk_bf16_f32 v23, v23, v24
	s_nop 1
	v_cndmask_b32_e64 v18, v18, 0, s[58:59]
	v_readlane_b32 s58, v237, 30
	v_readlane_b32 s59, v237, 31
	s_nop 1
	v_cndmask_b32_e64 v19, v19, 0, s[58:59]
	v_readlane_b32 s58, v237, 32
	v_readlane_b32 s59, v237, 33
	v_cvt_pk_bf16_f32 v24, v18, v19
	s_nop 1
	v_cndmask_b32_e64 v18, v20, 0, s[58:59]
	v_readlane_b32 s58, v237, 34
	v_readlane_b32 s59, v237, 35
	s_nop 1
	v_cndmask_b32_e64 v19, v21, 0, s[58:59]
	v_cvt_pk_bf16_f32 v25, v18, v19
	ds_write_b128 v120, v[22:25] offset:34816
	s_nop 0
	s_nop 0
	v_readlane_b32 s58, v237, 36
	v_readlane_b32 s59, v237, 37
	s_nop 0
	s_nop 0
	v_cndmask_b32_e64 v22, v208, 0, s[58:59]
	v_readlane_b32 s58, v237, 38
	v_readlane_b32 s59, v237, 39
	s_nop 1
	v_cndmask_b32_e64 v23, 0, v209, s[58:59]
	v_readlane_b32 s58, v237, 40
	v_readlane_b32 s59, v237, 41
	v_cvt_pk_bf16_f32 v22, v22, v23
	s_nop 1
	v_cndmask_b32_e64 v23, v210, 0, s[58:59]
	v_readlane_b32 s58, v237, 42
	v_readlane_b32 s59, v237, 43
	s_nop 1
	v_cndmask_b32_e64 v24, v211, 0, s[58:59]
	v_readlane_b32 s58, v237, 44
	v_readlane_b32 s59, v237, 45
	v_cvt_pk_bf16_f32 v23, v23, v24
	s_nop 1
	v_cndmask_b32_e64 v18, v204, 0, s[58:59]
	v_readlane_b32 s58, v237, 46
	v_readlane_b32 s59, v237, 47
	s_nop 1
	v_cndmask_b32_e64 v19, v205, 0, s[58:59]
	v_readlane_b32 s58, v237, 48
	v_readlane_b32 s59, v237, 49
	v_cvt_pk_bf16_f32 v24, v18, v19
	s_nop 1
	v_cndmask_b32_e64 v18, v206, 0, s[58:59]
	v_readlane_b32 s58, v237, 50
	v_readlane_b32 s59, v237, 51
	s_nop 1
	v_cndmask_b32_e64 v19, v207, 0, s[58:59]
	v_cvt_pk_bf16_f32 v25, v18, v19
	ds_write_b128 v120, v[22:25] offset:34832
	s_nop 0
	s_nop 0
	v_readlane_b32 s58, v237, 52
	v_readlane_b32 s59, v237, 53
	s_nop 0
	s_nop 0
	v_cndmask_b32_e64 v22, v216, 0, s[58:59]
	v_readlane_b32 s58, v237, 54
	v_readlane_b32 s59, v237, 55
	s_nop 1
	v_cndmask_b32_e64 v23, 0, v217, s[58:59]
	v_readlane_b32 s58, v237, 56
	v_readlane_b32 s59, v237, 57
	v_cvt_pk_bf16_f32 v22, v22, v23
	s_nop 1
	v_cndmask_b32_e64 v23, v218, 0, s[58:59]
	v_readlane_b32 s58, v237, 58
	v_readlane_b32 s59, v237, 59
	s_nop 1
	v_cndmask_b32_e64 v24, v219, 0, s[58:59]
	v_readlane_b32 s58, v237, 60
	v_readlane_b32 s59, v237, 61
	v_cvt_pk_bf16_f32 v23, v23, v24
	s_nop 1
	v_cndmask_b32_e64 v18, v212, 0, s[58:59]
	v_readlane_b32 s58, v237, 62
	v_readlane_b32 s59, v237, 63
	s_nop 1
	v_cndmask_b32_e64 v19, v213, 0, s[58:59]
	v_readlane_b32 s58, v236, 0
	v_readlane_b32 s59, v236, 1
	v_cvt_pk_bf16_f32 v24, v18, v19
	s_nop 1
	v_cndmask_b32_e64 v18, v214, 0, s[58:59]
	v_readlane_b32 s58, v236, 2
	v_readlane_b32 s59, v236, 3
	s_nop 1
	v_cndmask_b32_e64 v19, v215, 0, s[58:59]
	v_cvt_pk_bf16_f32 v25, v18, v19
	ds_write_b128 v120, v[22:25] offset:34848
	s_nop 0
	s_nop 0
	v_readlane_b32 s58, v236, 4
	v_readlane_b32 s59, v236, 5
	s_nop 0
	v_cndmask_b32_e64 v18, v220, 0, s[68:69]
	s_nop 0
	v_cndmask_b32_e64 v16, v224, 0, s[58:59]
	v_readlane_b32 s58, v236, 6
	v_readlane_b32 s59, v236, 7
	v_cndmask_b32_e64 v19, v221, 0, s[70:71]
	v_cvt_pk_bf16_f32 v18, v18, v19
	v_cndmask_b32_e64 v19, v222, 0, s[72:73]
	v_cndmask_b32_e64 v17, 0, v225, s[58:59]
	v_readlane_b32 s58, v236, 8
	v_readlane_b32 s59, v236, 9
	v_cvt_pk_bf16_f32 v16, v16, v17
	v_cndmask_b32_e64 v22, v227, 0, s[66:67]
	v_cndmask_b32_e64 v20, v223, 0, s[74:75]
	v_cndmask_b32_e64 v17, v226, 0, s[58:59]
	v_cvt_pk_bf16_f32 v17, v17, v22
	v_cvt_pk_bf16_f32 v19, v19, v20
	ds_write_b128 v120, v[16:19] offset:34864

; #define LAS __attribute__((address_space(3)))
; __device__ __forceinline__ float bf2f(unsigned b) { return __uint_as_float(b << 16); }
; __device__ __forceinline__ unsigned pk2(float lo, float hi) { unsigned r; asm("v_cvt_pk_bf16_f32 %0, %1, %2" : "=v"(r) : "v"(lo), "v"(hi)); return r; }
; #define LBAR() do { asm volatile("s_waitcnt lgkmcnt(0)" ::: "memory"); __builtin_amdgcn_s_barrier(); asm volatile("" ::: "memory"); } while (0)
; __device__ __forceinline__ void sgu_prompt_item(int item, const u16* PROJ, u16* MIXIN, const float* gln, const float* bln, const float* wsp, const float* bsp, LAS unsigned char* lds, int& hh_cached) {
;     ...
;     LBAR();
;     { const int dc = tid & 127, sg = tid >> 7; const float g = gln[hh * 128 + dc], b = bln[hh * 128 + dc];
; #pragma unroll
;       for (int i = 0; i < 4; ++i) { const int s0 = sg * 32 + i * 8; float v[8];
; #pragma unroll
;           for (int j = 0; j < 8; ++j) { const f32x2 st = *(const LAS f32x2*)(STAT + 2 * (s0 + j)); v[j] = (bf2f(RAW[(s0 + j) * LD2 + dc]) - st.x) * st.y * g + b; }
;           u32x4 o; o.x = pk2(v[0], v[1]); o.y = pk2(v[2], v[3]); o.z = pk2(v[4], v[5]); o.w = pk2(v[6], v[7]);
;           *(LAS u32x4*)(VnT + dc * LD2 + s0) = o; } }
.LBB0_240:
	s_or_b64 exec, exec, s[80:81]
	v_or_b32_e32 v0, s35, v69
	s_waitcnt lgkmcnt(0)
	s_barrier
	v_mov_b32_e32 v16, v233
	v_mov_b32_e32 v17, v234
	s_add_i32 s6, 0, 0x19800
	v_add_u32_e32 v0, s6, v121
	v_add_u32_e32 v4, s6, v122
	v_add_u32_e32 v8, s6, v123
	v_add_u32_e32 v12, s6, v124
	ds_read_u16 v18, v150 offset:816
	ds_read_u16 v19, v150 offset:1088
	ds_read_u16 v20, v150 offset:1360
	ds_read_u16 v21, v150 offset:1632
	ds_read_u16 v22, v150 offset:1904
	s_waitcnt lgkmcnt(5)
	ds_read_b128 v[0:3], v0
	ds_read_u16 v27, v150
	ds_read_u16 v28, v150 offset:272
	ds_read_u16 v29, v150 offset:544
	ds_read_b128 v[4:7], v4
	ds_read_b128 v[8:11], v8
	ds_read_b128 v[12:15], v12
	s_waitcnt lgkmcnt(11)
	v_lshlrev_b32_e32 v18, 16, v18
	s_waitcnt lgkmcnt(5)
	v_lshlrev_b32_e32 v27, 16, v27
	s_waitcnt lgkmcnt(4)
	v_lshlrev_b32_e32 v28, 16, v28
	s_waitcnt lgkmcnt(3)
	v_lshlrev_b32_e32 v29, 16, v29
	v_lshlrev_b32_e32 v19, 16, v19
	v_lshlrev_b32_e32 v20, 16, v20
	v_lshlrev_b32_e32 v21, 16, v21
	v_lshlrev_b32_e32 v22, 16, v22
	s_waitcnt lgkmcnt(2)
	v_sub_f32_e32 v6, v18, v6
	v_sub_f32_e32 v0, v27, v0
	v_sub_f32_e32 v2, v28, v2
	v_sub_f32_e32 v4, v29, v4
	s_waitcnt lgkmcnt(1)
	v_sub_f32_e32 v8, v19, v8
	v_sub_f32_e32 v10, v20, v10
	s_waitcnt lgkmcnt(0)
	v_sub_f32_e32 v12, v21, v12
	v_sub_f32_e32 v14, v22, v14
	v_mul_f32_e32 v6, v7, v6
	v_mul_f32_e32 v0, v1, v0
	v_mul_f32_e32 v1, v3, v2
	v_mul_f32_e32 v2, v5, v4
	v_mul_f32_e32 v7, v9, v8
	v_mul_f32_e32 v8, v11, v10
	v_mul_f32_e32 v9, v13, v12
	v_mul_f32_e32 v10, v15, v14
	v_add_u32_e32 v23, s6, v126
	v_add_u32_e32 v24, s6, v127
	v_add_u32_e32 v25, s6, v130
	v_add_u32_e32 v26, s6, v131
	v_mov_b32_e32 v81, v141
	s_waitcnt vmcnt(0)
	v_fma_f32 v0, v16, v0, v17
	v_fma_f32 v1, v16, v1, v17
	v_fma_f32 v2, v16, v2, v17
	v_fma_f32 v3, v16, v6, v17
	v_fma_f32 v4, v16, v7, v17
	v_fma_f32 v5, v16, v8, v17
	v_fma_f32 v6, v16, v9, v17
	v_fma_f32 v7, v16, v10, v17
	v_cvt_pk_bf16_f32 v0, v0, v1
	v_cvt_pk_bf16_f32 v1, v2, v3
	v_cvt_pk_bf16_f32 v2, v4, v5
	v_cvt_pk_bf16_f32 v3, v6, v7
	ds_write_b128 v125, v[0:3]
	ds_read_b128 v[0:3], v23
	ds_read_b128 v[4:7], v24
	ds_read_b128 v[8:11], v25
	ds_read_b128 v[12:15], v26
	ds_read_u16 v18, v150 offset:2176
	ds_read_u16 v19, v150 offset:2448
	ds_read_u16 v20, v150 offset:2720
	ds_read_u16 v21, v150 offset:2992
	ds_read_u16 v22, v150 offset:3264
	ds_read_u16 v23, v150 offset:3536
	ds_read_u16 v24, v150 offset:3808
	ds_read_u16 v25, v150 offset:4080
	s_waitcnt lgkmcnt(7)
	v_lshlrev_b32_e32 v18, 16, v18
	s_waitcnt lgkmcnt(6)
	v_lshlrev_b32_e32 v19, 16, v19
	s_waitcnt lgkmcnt(5)
	v_lshlrev_b32_e32 v20, 16, v20
	s_waitcnt lgkmcnt(4)
	v_lshlrev_b32_e32 v21, 16, v21
	v_sub_f32_e32 v0, v18, v0
	v_sub_f32_e32 v2, v19, v2
	v_sub_f32_e32 v4, v20, v4
	v_sub_f32_e32 v6, v21, v6
	s_waitcnt lgkmcnt(3)
	v_lshlrev_b32_e32 v22, 16, v22
	v_mul_f32_e32 v0, v1, v0
	v_mul_f32_e32 v1, v3, v2
	v_mul_f32_e32 v2, v5, v4
	v_mul_f32_e32 v3, v7, v6
	s_waitcnt lgkmcnt(2)
	v_lshlrev_b32_e32 v5, 16, v23
	s_waitcnt lgkmcnt(1)
	v_lshlrev_b32_e32 v6, 16, v24
	s_waitcnt lgkmcnt(0)
	v_lshlrev_b32_e32 v7, 16, v25
	v_fma_f32 v0, v16, v0, v17
	v_sub_f32_e32 v4, v22, v8
	v_sub_f32_e32 v5, v5, v10
	v_sub_f32_e32 v6, v6, v12
	v_sub_f32_e32 v7, v7, v14
	v_fma_f32 v1, v16, v1, v17
	v_fma_f32 v2, v16, v2, v17
	v_fma_f32 v3, v16, v3, v17
	v_mul_f32_e32 v4, v9, v4
	v_mul_f32_e32 v5, v11, v5
	v_mul_f32_e32 v6, v13, v6
	v_mul_f32_e32 v7, v15, v7
	v_cvt_pk_bf16_f32 v0, v0, v1
	v_fma_f32 v4, v16, v4, v17
	v_fma_f32 v5, v16, v5, v17
	v_fma_f32 v6, v16, v6, v17
	v_fma_f32 v7, v16, v7, v17
	v_cvt_pk_bf16_f32 v1, v2, v3
	v_cvt_pk_bf16_f32 v2, v4, v5
	v_cvt_pk_bf16_f32 v3, v6, v7
	ds_write_b128 v125, v[0:3] offset:16
	v_add_u32_e32 v0, s6, v132
	ds_read_b128 v[0:3], v0
	ds_read_u16 v4, v150 offset:4352
	ds_read_u16 v8, v150 offset:4624
	ds_read_u16 v9, v150 offset:4896
	ds_read_u16 v10, v150 offset:5168
	ds_read_u16 v11, v150 offset:5440
	ds_read_u16 v12, v150 offset:5712
	ds_read_u16 v13, v150 offset:5984
	ds_read_u16 v14, v150 offset:6256
	s_waitcnt lgkmcnt(7)
; #define LAS __attribute__((address_space(3)))
; __device__ __forceinline__ float bf2f(unsigned b) { return __uint_as_float(b << 16); }
; __device__ __forceinline__ unsigned pk2(float lo, float hi) { unsigned r; asm("v_cvt_pk_bf16_f32 %0, %1, %2" : "=v"(r) : "v"(lo), "v"(hi)); return r; }
; #define LBAR() do { asm volatile("s_waitcnt lgkmcnt(0)" ::: "memory"); __builtin_amdgcn_s_barrier(); asm volatile("" ::: "memory"); } while (0)
; __device__ __forceinline__ void sgu_prompt_item(int item, const u16* PROJ, u16* MIXIN, const float* gln, const float* bln, const float* wsp, const float* bsp, LAS unsigned char* lds, int& hh_cached) {
;     ...
;     { const int dc = tid & 127, sg = tid >> 7; const float g = gln[hh * 128 + dc], b = bln[hh * 128 + dc];
; #pragma unroll
;       for (int i = 0; i < 4; ++i) { const int s0 = sg * 32 + i * 8; float v[8];
; #pragma unroll
;           for (int j = 0; j < 8; ++j) { const f32x2 st = *(const LAS f32x2*)(STAT + 2 * (s0 + j)); v[j] = (bf2f(RAW[(s0 + j) * LD2 + dc]) - st.x) * st.y * g + b; }
;           u32x4 o; o.x = pk2(v[0], v[1]); o.y = pk2(v[2], v[3]); o.z = pk2(v[4], v[5]); o.w = pk2(v[6], v[7]);
;           *(LAS u32x4*)(VnT + dc * LD2 + s0) = o; } }
;     LBAR();
;     f32x4 acc[8];
; #pragma unroll
;     for (int dct = 0; dct < 8; ++dct) acc[dct] = (f32x4){0.f, 0.f, 0.f, 0.f};
	v_lshlrev_b32_e32 v15, 16, v4
	v_add_u32_e32 v4, s6, v133
	v_sub_f32_e32 v0, v15, v0
	ds_read_b128 v[4:7], v4
	v_mul_f32_e32 v0, v1, v0
	v_fma_f32 v15, v16, v0, v17
	s_waitcnt lgkmcnt(7)
	v_lshlrev_b32_e32 v0, 16, v8
	v_sub_f32_e32 v0, v0, v2
	v_mul_f32_e32 v0, v3, v0
	v_fma_f32 v8, v16, v0, v17
	s_waitcnt lgkmcnt(6)
	v_lshlrev_b32_e32 v0, 16, v9
	s_waitcnt lgkmcnt(0)
	v_sub_f32_e32 v0, v0, v4
	v_mul_f32_e32 v0, v5, v0
	v_fma_f32 v9, v16, v0, v17
	v_lshlrev_b32_e32 v0, 16, v10
	v_sub_f32_e32 v0, v0, v6
	v_mul_f32_e32 v4, v7, v0
	v_add_u32_e32 v0, s6, v134
	ds_read_b128 v[0:3], v0
	v_fma_f32 v10, v16, v4, v17
	v_lshlrev_b32_e32 v11, 16, v11
	v_add_u32_e32 v4, s6, v135
	ds_read_b128 v[4:7], v4
	s_waitcnt lgkmcnt(1)
	v_sub_f32_e32 v0, v11, v0
	v_mul_f32_e32 v0, v1, v0
	v_fma_f32 v11, v16, v0, v17
	v_lshlrev_b32_e32 v0, 16, v12
	v_sub_f32_e32 v0, v0, v2
	v_mul_f32_e32 v0, v3, v0
	v_fma_f32 v2, v16, v0, v17
	v_lshlrev_b32_e32 v0, 16, v13
	s_waitcnt lgkmcnt(0)
	v_sub_f32_e32 v0, v0, v4
	v_mul_f32_e32 v0, v5, v0
	v_fma_f32 v3, v16, v0, v17
	v_lshlrev_b32_e32 v0, 16, v14
	v_sub_f32_e32 v0, v0, v6
	v_mul_f32_e32 v0, v7, v0
	v_fma_f32 v4, v16, v0, v17
	v_cvt_pk_bf16_f32 v0, v15, v8
	v_cvt_pk_bf16_f32 v1, v9, v10
	v_cvt_pk_bf16_f32 v2, v11, v2
	v_cvt_pk_bf16_f32 v3, v3, v4
	ds_write_b128 v125, v[0:3] offset:32
	v_add_u32_e32 v0, s6, v136
	ds_read_b128 v[0:3], v0
	ds_read_u16 v4, v150 offset:6528
	ds_read_u16 v8, v150 offset:6800
	ds_read_u16 v9, v150 offset:7072
	ds_read_u16 v10, v150 offset:7344
	ds_read_u16 v11, v150 offset:7616
	ds_read_u16 v12, v150 offset:7888
	ds_read_u16 v13, v150 offset:8160
	s_waitcnt lgkmcnt(6)
	v_lshlrev_b32_e32 v14, 16, v4
	v_add_u32_e32 v4, s6, v137
	v_sub_f32_e32 v0, v14, v0
	ds_read_b128 v[4:7], v4
	v_mul_f32_e32 v0, v1, v0
	v_fma_f32 v14, v16, v0, v17
	s_waitcnt lgkmcnt(6)
	v_lshlrev_b32_e32 v0, 16, v8
	v_sub_f32_e32 v0, v0, v2
	v_mul_f32_e32 v0, v3, v0
	v_fma_f32 v8, v16, v0, v17
	s_waitcnt lgkmcnt(5)
	v_lshlrev_b32_e32 v0, 16, v9
	s_waitcnt lgkmcnt(0)
	v_sub_f32_e32 v0, v0, v4
	v_mul_f32_e32 v0, v5, v0
	v_fma_f32 v9, v16, v0, v17
	v_lshlrev_b32_e32 v0, 16, v10
	v_sub_f32_e32 v0, v0, v6
	v_mul_f32_e32 v4, v7, v0
	v_add_u32_e32 v0, s6, v138
	ds_read_b128 v[0:3], v0
	v_fma_f32 v6, v16, v4, v17
	v_lshlrev_b32_e32 v7, 16, v11
	v_add_u32_e32 v4, s6, v139
	ds_read_b64 v[4:5], v4
	s_waitcnt lgkmcnt(1)
	v_sub_f32_e32 v0, v7, v0
	v_mul_f32_e32 v0, v1, v0
	v_fma_f32 v7, v16, v0, v17
	v_lshlrev_b32_e32 v0, 16, v12
	v_sub_f32_e32 v0, v0, v2
	v_mul_f32_e32 v0, v3, v0
	v_fma_f32 v2, v16, v0, v17
	v_add_u32_e32 v0, s6, v140
	ds_read_b64 v[0:1], v0
	ds_read_u16 v3, v151
	v_lshlrev_b32_e32 v10, 16, v13
	s_waitcnt lgkmcnt(2)
	v_sub_f32_e32 v4, v10, v4
	v_mul_f32_e32 v4, v5, v4
	v_fma_f32 v4, v16, v4, v17
	s_waitcnt lgkmcnt(0)
	v_lshlrev_b32_e32 v3, 16, v3
	v_sub_f32_e32 v0, v3, v0
	v_mul_f32_e32 v0, v1, v0
	v_fmac_f32_e32 v17, v16, v0
	v_cvt_pk_bf16_f32 v0, v14, v8
	v_cvt_pk_bf16_f32 v1, v9, v6
	v_cvt_pk_bf16_f32 v2, v7, v2
	v_cvt_pk_bf16_f32 v3, v4, v17
	ds_write_b128 v125, v[0:3] offset:48
	s_waitcnt lgkmcnt(0)
	s_barrier
	s_lshr_b32 s6, s55, 7
	s_lshr_b32 s55, s55, 6
	s_mulk_i32 s55, 0x1100
	v_mov_b32_e32 v0, 0
	s_add_i32 s6, s6, 1
	v_add_u32_e32 v52, s55, v143
	v_mov_b32_e32 v1, v0
	v_mov_b32_e32 v2, v0
	v_mov_b32_e32 v3, v0
	v_mov_b32_e32 v4, v0
	v_mov_b32_e32 v5, v0
	v_mov_b32_e32 v6, v0
	v_mov_b32_e32 v7, v0
	v_mov_b32_e32 v8, v0
	v_mov_b32_e32 v9, v0
	v_mov_b32_e32 v10, v0
	v_mov_b32_e32 v11, v0
	v_mov_b32_e32 v12, v0
	v_mov_b32_e32 v13, v0
	v_mov_b32_e32 v14, v0
	v_mov_b32_e32 v15, v0
	v_mov_b32_e32 v16, v0
	v_mov_b32_e32 v17, v0
	v_mov_b32_e32 v18, v0
	v_mov_b32_e32 v19, v0
	v_mov_b32_e32 v20, v0
	v_mov_b32_e32 v21, v0
	v_mov_b32_e32 v22, v0
	v_mov_b32_e32 v23, v0
	v_mov_b32_e32 v24, v0
	v_mov_b32_e32 v25, v0
	v_mov_b32_e32 v26, v0
	v_mov_b32_e32 v27, v0
	v_mov_b32_e32 v28, v0
	v_mov_b32_e32 v29, v0
	v_mov_b32_e32 v30, v0
	v_mov_b32_e32 v31, v0
